# v19 + attention-B output stage: the 16 serialized sub-LN gain loads hoisted into dead accumulator registers, single wait
# baseline (speedup 1.0000x reference)
.LBB0_64:
	s_or_b64 exec, exec, s[46:47]
	s_waitcnt lgkmcnt(0)
	s_barrier
	global_load_dwordx4 v[24:27], v[198:199], off
	global_load_dwordx4 v[28:31], v[198:199], off offset:32
	global_load_dwordx4 v[32:35], v[198:199], off offset:64
	global_load_dwordx4 v[36:39], v[198:199], off offset:96
	global_load_dwordx4 v[40:43], v[198:199], off offset:128
	global_load_dwordx4 v[44:47], v[198:199], off offset:160
	global_load_dwordx4 v[48:51], v[198:199], off offset:192
	global_load_dwordx4 v[52:55], v[198:199], off offset:224
	global_load_dwordx4 v[56:59], v[198:199], off offset:256
	global_load_dwordx4 v[60:63], v[198:199], off offset:288
	global_load_dwordx4 v[64:67], v[198:199], off offset:320
	global_load_dwordx4 v[68:71], v[198:199], off offset:352
	global_load_dwordx4 v[72:75], v[198:199], off offset:384
	global_load_dwordx4 v[76:79], v[198:199], off offset:416
	global_load_dwordx4 v[80:83], v[198:199], off offset:448
	global_load_dwordx4 v[84:87], v[198:199], off offset:480
	v_add_u32_e32 v16, s21, v235
	ds_read_b32 v16, v16
	s_mov_b64 s[46:47], 0
	s_waitcnt lgkmcnt(0)
	v_add_f32_e32 v1, v1, v16
	v_fmamk_f32 v1, v1, 0x3b800000, v215
	v_mul_f32_e32 v16, 0x4b800000, v1
	v_cmp_gt_f32_e32 vcc, s65, v1
	s_nop 1
	v_cndmask_b32_e32 v1, v1, v16, vcc
	v_rsq_f32_e32 v1, v1
	v_lshl_add_u64 v[16:17], v[206:207], 1, v[204:205]
	v_mul_f32_e32 v18, 0x45800000, v1
	v_cndmask_b32_e32 v1, v1, v18, vcc
	v_mul_f32_e32 v18, 0x3f24fd5c, v1
	v_pk_mul_f32 v[8:9], v[8:9], v[18:19] op_sel_hi:[1,0]
	v_pk_mul_f32 v[6:7], v[6:7], v[18:19] op_sel_hi:[1,0]
	v_pk_mul_f32 v[2:3], v[2:3], v[18:19] op_sel_hi:[1,0]
	v_pk_mul_f32 v[4:5], v[4:5], v[18:19] op_sel_hi:[1,0]
	s_and_b64 vcc, exec, s[12:13]
	s_waitcnt vmcnt(0)
	v_pk_mul_f32 v[8:9], v[24:25], v[8:9]
	v_pk_mul_f32 v[6:7], v[26:27], v[6:7]
	v_cvt_pk_bf16_f32 v8, v8, v9
	v_cvt_pk_bf16_f32 v9, v6, v7
	global_store_dwordx2 v[16:17], v[8:9], off
	v_pk_mul_f32 v[2:3], v[28:29], v[2:3]
	v_pk_mul_f32 v[4:5], v[30:31], v[4:5]
	v_cvt_pk_bf16_f32 v2, v2, v3
	v_cvt_pk_bf16_f32 v3, v4, v5
	global_store_dwordx2 v[16:17], v[2:3], off offset:16
	v_pk_mul_f32 v[6:7], v[14:15], v[18:19] op_sel_hi:[1,0]
	v_pk_mul_f32 v[8:9], v[12:13], v[18:19] op_sel_hi:[1,0]
	v_pk_mul_f32 v[2:3], v[32:33], v[6:7]
	v_pk_mul_f32 v[4:5], v[34:35], v[8:9]
	v_cvt_pk_bf16_f32 v2, v2, v3
	v_cvt_pk_bf16_f32 v3, v4, v5
	global_store_dwordx2 v[16:17], v[2:3], off offset:32
	v_pk_mul_f32 v[6:7], v[10:11], v[18:19] op_sel_hi:[1,0]
	v_pk_mul_f32 v[8:9], v[148:149], v[18:19] op_sel_hi:[1,0]
	v_pk_mul_f32 v[2:3], v[36:37], v[6:7]
	v_pk_mul_f32 v[4:5], v[38:39], v[8:9]
	v_cvt_pk_bf16_f32 v2, v2, v3
	v_cvt_pk_bf16_f32 v3, v4, v5
	global_store_dwordx2 v[16:17], v[2:3], off offset:48
	v_pk_mul_f32 v[6:7], v[154:155], v[18:19] op_sel_hi:[1,0]
	v_pk_mul_f32 v[8:9], v[152:153], v[18:19] op_sel_hi:[1,0]
	v_pk_mul_f32 v[2:3], v[40:41], v[6:7]
	v_pk_mul_f32 v[4:5], v[42:43], v[8:9]
	v_cvt_pk_bf16_f32 v2, v2, v3
	v_cvt_pk_bf16_f32 v3, v4, v5
	global_store_dwordx2 v[16:17], v[2:3], off offset:64
	v_pk_mul_f32 v[6:7], v[146:147], v[18:19] op_sel_hi:[1,0]
	v_pk_mul_f32 v[8:9], v[150:151], v[18:19] op_sel_hi:[1,0]
	v_pk_mul_f32 v[2:3], v[6:7], v[44:45]
	v_pk_mul_f32 v[4:5], v[8:9], v[46:47]
	v_cvt_pk_bf16_f32 v2, v2, v3
	v_cvt_pk_bf16_f32 v3, v4, v5
	global_store_dwordx2 v[16:17], v[2:3], off offset:80
	v_pk_mul_f32 v[6:7], v[160:161], v[18:19] op_sel_hi:[1,0]
	v_pk_mul_f32 v[8:9], v[158:159], v[18:19] op_sel_hi:[1,0]
	v_pk_mul_f32 v[2:3], v[6:7], v[48:49]
	v_pk_mul_f32 v[4:5], v[8:9], v[50:51]
	v_cvt_pk_bf16_f32 v2, v2, v3
	v_cvt_pk_bf16_f32 v3, v4, v5
	global_store_dwordx2 v[16:17], v[2:3], off offset:96
	v_pk_mul_f32 v[6:7], v[156:157], v[18:19] op_sel_hi:[1,0]
	v_pk_mul_f32 v[8:9], v[162:163], v[18:19] op_sel_hi:[1,0]
	v_pk_mul_f32 v[2:3], v[6:7], v[52:53]
	v_pk_mul_f32 v[4:5], v[8:9], v[54:55]
	v_cvt_pk_bf16_f32 v2, v2, v3
	v_cvt_pk_bf16_f32 v3, v4, v5
	global_store_dwordx2 v[16:17], v[2:3], off offset:112
	v_pk_mul_f32 v[6:7], v[170:171], v[18:19] op_sel_hi:[1,0]
	v_pk_mul_f32 v[8:9], v[168:169], v[18:19] op_sel_hi:[1,0]
	v_pk_mul_f32 v[2:3], v[6:7], v[56:57]
	v_pk_mul_f32 v[4:5], v[8:9], v[58:59]
	v_cvt_pk_bf16_f32 v2, v2, v3
	v_cvt_pk_bf16_f32 v3, v4, v5
	global_store_dwordx2 v[16:17], v[2:3], off offset:128
	v_pk_mul_f32 v[6:7], v[164:165], v[18:19] op_sel_hi:[1,0]
	v_pk_mul_f32 v[8:9], v[166:167], v[18:19] op_sel_hi:[1,0]
	v_pk_mul_f32 v[2:3], v[6:7], v[60:61]
	v_pk_mul_f32 v[4:5], v[8:9], v[62:63]
	v_cvt_pk_bf16_f32 v2, v2, v3
	v_cvt_pk_bf16_f32 v3, v4, v5
	global_store_dwordx2 v[16:17], v[2:3], off offset:144
	v_pk_mul_f32 v[6:7], v[176:177], v[18:19] op_sel_hi:[1,0]
	v_pk_mul_f32 v[8:9], v[174:175], v[18:19] op_sel_hi:[1,0]
	v_pk_mul_f32 v[2:3], v[6:7], v[64:65]
	v_pk_mul_f32 v[4:5], v[8:9], v[66:67]
	v_cvt_pk_bf16_f32 v2, v2, v3
	v_cvt_pk_bf16_f32 v3, v4, v5
	global_store_dwordx2 v[16:17], v[2:3], off offset:160
	v_pk_mul_f32 v[6:7], v[172:173], v[18:19] op_sel_hi:[1,0]
	v_pk_mul_f32 v[8:9], v[178:179], v[18:19] op_sel_hi:[1,0]
	v_pk_mul_f32 v[2:3], v[6:7], v[68:69]
	v_pk_mul_f32 v[4:5], v[8:9], v[70:71]
	v_cvt_pk_bf16_f32 v2, v2, v3
	v_cvt_pk_bf16_f32 v3, v4, v5
	global_store_dwordx2 v[16:17], v[2:3], off offset:176
	v_pk_mul_f32 v[6:7], v[186:187], v[18:19] op_sel_hi:[1,0]
	v_pk_mul_f32 v[8:9], v[184:185], v[18:19] op_sel_hi:[1,0]
	v_pk_mul_f32 v[2:3], v[6:7], v[72:73]
	v_pk_mul_f32 v[4:5], v[8:9], v[74:75]
	v_cvt_pk_bf16_f32 v2, v2, v3
	v_cvt_pk_bf16_f32 v3, v4, v5
	global_store_dwordx2 v[16:17], v[2:3], off offset:192
	v_pk_mul_f32 v[6:7], v[180:181], v[18:19] op_sel_hi:[1,0]
	v_pk_mul_f32 v[8:9], v[182:183], v[18:19] op_sel_hi:[1,0]
	v_pk_mul_f32 v[2:3], v[6:7], v[76:77]
	v_pk_mul_f32 v[4:5], v[8:9], v[78:79]
	v_cvt_pk_bf16_f32 v2, v2, v3
	v_cvt_pk_bf16_f32 v3, v4, v5
	global_store_dwordx2 v[16:17], v[2:3], off offset:208
	v_pk_mul_f32 v[6:7], v[208:209], v[18:19] op_sel_hi:[1,0]
	v_pk_mul_f32 v[8:9], v[190:191], v[18:19] op_sel_hi:[1,0]
	v_pk_mul_f32 v[2:3], v[6:7], v[80:81]
	v_pk_mul_f32 v[4:5], v[8:9], v[82:83]
	v_cvt_pk_bf16_f32 v2, v2, v3
	v_cvt_pk_bf16_f32 v3, v4, v5
	global_store_dwordx2 v[16:17], v[2:3], off offset:224
	v_pk_mul_f32 v[6:7], v[188:189], v[18:19] op_sel_hi:[1,0]
	v_pk_mul_f32 v[8:9], v[210:211], v[18:19] op_sel_hi:[1,0]
	v_pk_mul_f32 v[2:3], v[6:7], v[84:85]
	v_pk_mul_f32 v[4:5], v[8:9], v[86:87]
	v_cvt_pk_bf16_f32 v2, v2, v3
	v_cvt_pk_bf16_f32 v3, v4, v5
	global_store_dwordx2 v[16:17], v[2:3], off offset:240
	s_barrier
	s_cbranch_vccnz .LBB0_62
